# P0 XN loop: all sixteen row loads of a step issued before the first wait (hipcc had vmcnt(3) after four loads)
# speedup vs baseline: 1.0006x; 1.0006x over previous
; #define LAS __attribute__((address_space(3)))
; __global__ void __launch_bounds__(NWAVES * 64, 2) fwd_kernel(Args args) {
;     ...
;         for (;;) {
;             unsigned st_ = 0u; if (lane == 0) st_ = __hip_atomic_fetch_add((LAS unsigned*)(lds + MISC_OFF) + 13, 1u, __ATOMIC_RELAXED, __HIP_MEMORY_SCOPE_WORKGROUP);
;             const int st = (int)__builtin_amdgcn_readfirstlane(st_);
;             if (st >= nsteps) break;
;             const int m = 4 * (vcu * 8 + (st & 7)) + (st >> 3) * 4 * NGW;
;             if (m >= M) continue;
;             const f32x4* xr = (const f32x4*)(x + (size_t)m * D) + lane;
;             f32x4 v[4][4]; float s2[4] = {0.f, 0.f, 0.f, 0.f};
; #pragma unroll
;             for (int q = 0; q < 4; ++q)
; #pragma unroll
;                 for (int j = 0; j < 4; ++j) v[q][j] = __builtin_nontemporal_load(xr + q * (D / 4) + 64 * j);
; #pragma unroll
;             for (int q = 0; q < 4; ++q)
; #pragma unroll
;                 for (int j = 0; j < 4; ++j) s2[q] += (v[q][j][0] * v[q][j][0] + v[q][j][1] * v[q][j][1]) + (v[q][j][2] * v[q][j][2] + v[q][j][3] * v[q][j][3]);
;             wave_sum_n<4>(s2);
.LBB0_115:
	s_or_b64 exec, exec, s[4:5]
	v_readfirstlane_b32 s8, v2
	s_cmp_ge_i32 s8, s14
	s_mov_b64 s[4:5], -1
	s_cbranch_scc1 .LBB0_110
	s_and_b32 s4, s8, 7
	s_ashr_i32 s5, s8, 1
	s_or_b32 s4, s4, s26
	s_and_b32 s5, s5, -4
	s_lshl_b32 s4, s4, 2
	s_mul_i32 s5, s5, s68
	s_add_i32 s8, s4, s5
	s_cmpk_gt_i32 s8, 0x3fff
	s_cbranch_scc1 .LBB0_109
	s_ashr_i32 s9, s8, 31
	s_lshl_b64 s[4:5], s[8:9], 12
	v_lshl_add_u64 v[2:3], v[70:71], 0, s[4:5]
	global_load_dwordx4 v[62:65], v[2:3], off nt
	global_load_dwordx4 v[58:61], v[2:3], off offset:1024 nt
	global_load_dwordx4 v[54:57], v[2:3], off offset:2048 nt
	global_load_dwordx4 v[50:53], v[2:3], off offset:3072 nt
	v_add_co_u32_e32 v4, vcc, 0x1000, v2
	s_nop 1
	v_addc_co_u32_e32 v5, vcc, 0, v3, vcc
	global_load_dwordx4 v[46:49], v[4:5], off nt
	global_load_dwordx4 v[42:45], v[4:5], off offset:1024 nt
	global_load_dwordx4 v[38:41], v[4:5], off offset:2048 nt
	global_load_dwordx4 v[34:37], v[4:5], off offset:3072 nt
	v_add_co_u32_e32 v4, vcc, 0x2000, v2
	s_nop 1
	v_addc_co_u32_e32 v5, vcc, 0, v3, vcc
	global_load_dwordx4 v[30:33], v[4:5], off nt
	global_load_dwordx4 v[26:29], v[4:5], off offset:1024 nt
	global_load_dwordx4 v[22:25], v[4:5], off offset:2048 nt
	global_load_dwordx4 v[18:21], v[4:5], off offset:3072 nt
	v_add_co_u32_e32 v2, vcc, 0x3000, v2
	s_nop 1
	v_addc_co_u32_e32 v3, vcc, 0, v3, vcc
	global_load_dwordx4 v[14:17], v[2:3], off nt
	global_load_dwordx4 v[10:13], v[2:3], off offset:1024 nt
	global_load_dwordx4 v[6:9], v[2:3], off offset:2048 nt
	s_nop 0
	global_load_dwordx4 v[2:5], v[2:3], off offset:3072 nt
	s_waitcnt vmcnt(15)
	v_mul_f32_e32 v83, v63, v63
	v_mul_f32_e32 v84, v65, v65
	s_waitcnt vmcnt(14)
	v_mul_f32_e32 v85, v59, v59
	v_mul_f32_e32 v86, v61, v61
	s_waitcnt vmcnt(13)
	v_mul_f32_e32 v87, v55, v55
	v_mul_f32_e32 v88, v57, v57
	s_waitcnt vmcnt(12)
	v_mul_f32_e32 v89, v51, v51
	v_mul_f32_e32 v90, v53, v53
	v_fmac_f32_e32 v83, v62, v62
	v_fmac_f32_e32 v84, v64, v64
	v_fmac_f32_e32 v85, v58, v58
	v_fmac_f32_e32 v86, v60, v60
	v_fmac_f32_e32 v87, v54, v54
	v_fmac_f32_e32 v88, v56, v56
	v_fmac_f32_e32 v89, v50, v50
	v_fmac_f32_e32 v90, v52, v52
	v_add_f32_e32 v83, v83, v84
	v_add_f32_e32 v84, v85, v86
	v_add_f32_e32 v85, v87, v88
	v_add_f32_e32 v86, v89, v90
	v_add_f32_e32 v83, v83, v84
	v_add_f32_e32 v83, v83, v85
	v_add_f32_e32 v83, v83, v86
	v_cmp_lt_i32_e32 vcc, v77, v76
	s_waitcnt vmcnt(11)
	v_mul_f32_e32 v87, v47, v47
	v_mul_f32_e32 v88, v49, v49
	s_waitcnt vmcnt(10)
	v_mul_f32_e32 v89, v43, v43
	v_mul_f32_e32 v90, v45, v45
	v_fmac_f32_e32 v87, v46, v46
	v_fmac_f32_e32 v88, v48, v48
	s_waitcnt vmcnt(7)
	v_mul_f32_e32 v84, v31, v31
	v_mul_f32_e32 v95, v33, v33
	s_waitcnt vmcnt(6)
	v_mul_f32_e32 v96, v27, v27
	v_mul_f32_e32 v97, v29, v29
	v_fmac_f32_e32 v89, v42, v42
	v_fmac_f32_e32 v90, v44, v44
	v_fmac_f32_e32 v84, v30, v30
	v_fmac_f32_e32 v95, v32, v32
	v_fmac_f32_e32 v96, v26, v26
	v_fmac_f32_e32 v97, v28, v28
	v_add_f32_e32 v85, v87, v88
	v_add_f32_e32 v87, v89, v90
	v_add_f32_e32 v84, v84, v95
	v_add_f32_e32 v86, v96, v97
	v_add_f32_e32 v85, v85, v87
	v_add_f32_e32 v84, v84, v86
	s_waitcnt vmcnt(5)
	v_mul_f32_e32 v86, v23, v23
	v_mul_f32_e32 v87, v25, v25
	v_fmac_f32_e32 v86, v22, v22
	v_fmac_f32_e32 v87, v24, v24
	v_add_f32_e32 v86, v86, v87
	v_add_f32_e32 v84, v84, v86
	s_waitcnt vmcnt(4)
	v_mul_f32_e32 v86, v19, v19
	v_mul_f32_e32 v87, v21, v21
	v_fmac_f32_e32 v86, v18, v18
	v_fmac_f32_e32 v87, v20, v20
	v_mul_f32_e32 v91, v39, v39
	v_mul_f32_e32 v92, v41, v41
	v_add_f32_e32 v86, v86, v87
	v_fmac_f32_e32 v91, v38, v38
	v_fmac_f32_e32 v92, v40, v40
	v_add_f32_e32 v84, v84, v86
	s_waitcnt vmcnt(3)
	v_mul_f32_e32 v86, v15, v15
	v_mul_f32_e32 v87, v17, v17
	v_add_f32_e32 v88, v91, v92
	v_fmac_f32_e32 v86, v14, v14
	v_fmac_f32_e32 v87, v16, v16
	v_add_f32_e32 v85, v85, v88
	v_add_f32_e32 v86, v86, v87
	s_waitcnt vmcnt(2)
; template <int N> __device__ __forceinline__ void wave_sum_n(float (&v)[N]) {
; #pragma unroll
;     for (int o = 1; o < 64; o <<= 1) { float t[N];
; #pragma unroll
;         for (int i = 0; i < N; ++i) t[i] = __shfl_xor(v[i], o);
; #pragma unroll
;         for (int i = 0; i < N; ++i) v[i] += t[i]; }
; }
; __global__ void __launch_bounds__(NWAVES * 64, 2) fwd_kernel(Args args) {
;     ...
;             for (int q = 0; q < 4; ++q)
; #pragma unroll
;                 for (int j = 0; j < 4; ++j) s2[q] += (v[q][j][0] * v[q][j][0] + v[q][j][1] * v[q][j][1]) + (v[q][j][2] * v[q][j][2] + v[q][j][3] * v[q][j][3]);
;             wave_sum_n<4>(s2);
; #pragma unroll
;             for (int q = 0; q < 4; ++q) {
;                 const float rms = sqrtf(s2[q] * (1.0f / D) + EPS), rstd = 1.0f / rms;
;                 if (lane == 0) rinv0[m + q] = rms;
	v_mul_f32_e32 v87, v11, v11
	v_mul_f32_e32 v88, v13, v13
	v_fmac_f32_e32 v87, v10, v10
	v_fmac_f32_e32 v88, v12, v12
	v_add_f32_e32 v87, v87, v88
	v_add_f32_e32 v86, v86, v87
	s_waitcnt vmcnt(1)
	v_mul_f32_e32 v87, v7, v7
	v_mul_f32_e32 v88, v9, v9
	v_fmac_f32_e32 v87, v6, v6
	v_fmac_f32_e32 v88, v8, v8
	v_add_f32_e32 v87, v87, v88
	v_add_f32_e32 v86, v86, v87
	s_waitcnt vmcnt(0)
	v_mul_f32_e32 v87, v3, v3
	v_mul_f32_e32 v88, v5, v5
	v_mul_f32_e32 v93, v35, v35
	v_mul_f32_e32 v94, v37, v37
	v_fmac_f32_e32 v87, v2, v2
	v_fmac_f32_e32 v88, v4, v4
	v_fmac_f32_e32 v93, v34, v34
	v_fmac_f32_e32 v94, v36, v36
	v_add_f32_e32 v87, v87, v88
	v_cndmask_b32_e32 v88, v75, v77, vcc
	v_add_f32_e32 v89, v93, v94
	v_lshlrev_b32_e32 v88, 2, v88
	v_add_f32_e32 v85, v85, v89
	ds_bpermute_b32 v89, v88, v83
	v_add_f32_e32 v86, v86, v87
	v_cmp_lt_i32_e32 vcc, v78, v76
	ds_bpermute_b32 v90, v88, v85
	ds_bpermute_b32 v91, v88, v84
	ds_bpermute_b32 v87, v88, v86
	v_cndmask_b32_e32 v88, v75, v78, vcc
	s_waitcnt lgkmcnt(3)
	v_add_f32_e32 v83, v83, v89
	v_lshlrev_b32_e32 v88, 2, v88
	ds_bpermute_b32 v89, v88, v83
	s_waitcnt lgkmcnt(3)
	v_add_f32_e32 v85, v85, v90
	s_waitcnt lgkmcnt(2)
	v_add_f32_e32 v84, v84, v91
	s_waitcnt lgkmcnt(1)
	v_add_f32_e32 v86, v86, v87
	v_cmp_lt_i32_e32 vcc, v79, v76
	ds_bpermute_b32 v90, v88, v85
	ds_bpermute_b32 v91, v88, v84
	ds_bpermute_b32 v87, v88, v86
	v_cndmask_b32_e32 v88, v75, v79, vcc
	s_waitcnt lgkmcnt(3)
	v_add_f32_e32 v83, v83, v89
	v_lshlrev_b32_e32 v88, 2, v88
	ds_bpermute_b32 v89, v88, v83
	s_waitcnt lgkmcnt(3)
	v_add_f32_e32 v85, v85, v90
	s_waitcnt lgkmcnt(2)
	v_add_f32_e32 v84, v84, v91
	s_waitcnt lgkmcnt(1)
	v_add_f32_e32 v86, v86, v87
	v_cmp_lt_i32_e32 vcc, v80, v76
	ds_bpermute_b32 v90, v88, v85
	ds_bpermute_b32 v91, v88, v84
	ds_bpermute_b32 v87, v88, v86
	v_cndmask_b32_e32 v88, v75, v80, vcc
	s_waitcnt lgkmcnt(3)
	v_add_f32_e32 v83, v83, v89
	v_lshlrev_b32_e32 v88, 2, v88
	ds_bpermute_b32 v89, v88, v83
	s_waitcnt lgkmcnt(3)
	v_add_f32_e32 v85, v85, v90
	s_waitcnt lgkmcnt(2)
	v_add_f32_e32 v84, v84, v91
	s_waitcnt lgkmcnt(1)
	v_add_f32_e32 v86, v86, v87
	v_cmp_lt_i32_e32 vcc, v81, v76
	ds_bpermute_b32 v90, v88, v85
	ds_bpermute_b32 v91, v88, v84
	ds_bpermute_b32 v87, v88, v86
	v_cndmask_b32_e32 v88, v75, v81, vcc
	s_waitcnt lgkmcnt(3)
	v_add_f32_e32 v83, v83, v89
	v_lshlrev_b32_e32 v88, 2, v88
	ds_bpermute_b32 v89, v88, v83
	v_cmp_lt_i32_e32 vcc, v82, v76
	s_waitcnt lgkmcnt(3)
	v_add_f32_e32 v85, v85, v90
	s_waitcnt lgkmcnt(2)
	v_add_f32_e32 v84, v84, v91
	s_waitcnt lgkmcnt(1)
	v_add_f32_e32 v86, v86, v87
	s_waitcnt lgkmcnt(0)
	v_add_f32_e32 v89, v83, v89
	v_cndmask_b32_e32 v83, v75, v82, vcc
	v_lshlrev_b32_e32 v91, 2, v83
	ds_bpermute_b32 v87, v88, v85
	ds_bpermute_b32 v90, v88, v84
	ds_bpermute_b32 v92, v91, v89
	ds_bpermute_b32 v88, v88, v86
	s_waitcnt lgkmcnt(3)
	v_add_f32_e32 v87, v85, v87
	s_waitcnt lgkmcnt(2)
	v_add_f32_e32 v85, v84, v90
	s_waitcnt lgkmcnt(1)
	v_add_f32_e32 v84, v89, v92
	v_fmamk_f32 v84, v84, 0x3a800000, v68
	s_waitcnt lgkmcnt(0)
	v_add_f32_e32 v83, v86, v88
	v_mul_f32_e32 v86, 0x4f800000, v84
	v_cmp_gt_f32_e32 vcc, s16, v84
	ds_bpermute_b32 v88, v91, v87
	s_nop 0
	v_cndmask_b32_e32 v89, v84, v86, vcc
	v_sqrt_f32_e32 v90, v89
	ds_bpermute_b32 v86, v91, v85
	ds_bpermute_b32 v84, v91, v83
	v_add_u32_e32 v91, -1, v90
	v_fma_f32 v92, -v91, v90, v89
	v_cmp_ge_f32_e64 s[4:5], 0, v92
	v_add_u32_e32 v92, 1, v90
	s_nop 0
	v_cndmask_b32_e64 v91, v90, v91, s[4:5]
	v_fma_f32 v90, -v92, v90, v89
	v_cmp_lt_f32_e64 s[4:5], 0, v90
	s_nop 1
	v_cndmask_b32_e64 v90, v91, v92, s[4:5]
	v_mul_f32_e32 v91, 0x37800000, v90
	v_cndmask_b32_e32 v90, v90, v91, vcc
	v_cmp_class_f32_e32 vcc, v89, v74
	s_nop 1
	v_cndmask_b32_e32 v89, v90, v89, vcc
	s_and_saveexec_b64 s[4:5], s[2:3]
	s_cbranch_execz .LBB0_119
	s_lshl_b64 s[12:13], s[8:9], 2
	s_add_u32 s12, s86, s12
	s_addc_u32 s13, s87, s13
	global_store_dword v69, v89, s[12:13]
